# as previous with merge-epilogue gate prefetch two row groups ahead (three buffers)
# speedup vs baseline: 1.0072x; 1.0009x over previous
; __device__ __forceinline__ unsigned cvt_pk_bf16(float lo, float hi) { unsigned r; asm volatile("v_cvt_pk_bf16_f32 %0, %1, %2" : "=v"(r) : "v"(lo), "v"(hi)); return r; }
;     __device__ __forceinline__ void operator()(f32x4 (&acc)[2][2][4][2], const Unit& u, int wr, int wc, int fr, int fq) const {
;         const int row0 = u.pm * BM + wr * 64 + fr; const int col0 = u.pn * BM + wc * 32 + 8 * fq; const int br = u.seg;
; #pragma unroll
;         for (int ai = 0; ai < 2; ++ai)
; #pragma unroll
;             for (int m = 0; m < 4; ++m) { const size_t row = (size_t)(row0 + ai * HALF + m * 16);
; #pragma unroll
;                 for (int bj = 0; bj < 2; ++bj) { const int col = col0 + bj * HALF;
;                     const u32x4 g = *(const u32x4*)(PG + row * 6144 + br * D + col);
;                     float s[8] = {bflo(g[0]), bfhi(g[0]), bflo(g[1]), bfhi(g[1]), bflo(g[2]), bfhi(g[2]), bflo(g[3]), bfhi(g[3])};
;                     if (br < 2) { const u32x4 h = *(const u32x4*)(PG + row * 6144 + (br + 1) * D + col);
;                         const float d[8] = {bflo(h[0]), bfhi(h[0]), bflo(h[1]), bfhi(h[1]), bflo(h[2]), bfhi(h[2]), bflo(h[3]), bfhi(h[3])};
; #pragma unroll
;                         for (int j = 0; j < 8; ++j) s[j] = s[j] * __builtin_amdgcn_rcpf(fmaxf(d[j], 1e-30f)); }
;                     f32x4& v0 = acc[ai][bj][m][0]; f32x4& v1 = acc[ai][bj][m][1];
; #pragma unroll
;                     for (int j = 0; j < 4; ++j) { v0[j] *= s[j]; v1[j] *= s[4 + j]; }
;                     if (br == 2) { u32x4 w; w.x = cvt_pk_bf16(v0[0], v0[1]); w.y = cvt_pk_bf16(v0[2], v0[3]); w.z = cvt_pk_bf16(v1[0], v1[1]); w.w = cvt_pk_bf16(v1[2], v1[3]);
;                         *(u32x4*)(MG + row * D + col) = w; } } }
;     }
.LBB0_1607:
	v_lshl_add_u32 v156, s24, 8, v1
	s_lshl_b32 s26, s35, 11
	v_mov_b64_e32 v[130:131], s[6:7]
	s_movk_i32 s2, 0x3000
	v_lshl_or_b32 v154, s20, 8, v173
	s_ashr_i32 s27, s26, 31
	v_mad_i64_i32 v[130:131], s[2:3], v156, s2, v[130:131]
	v_lshl_add_u64 v[134:135], s[26:27], 1, v[130:131]
	v_ashrrev_i32_e32 v155, 31, v154
	v_lshl_add_u64 v[162:163], v[154:155], 1, v[134:135]
	v_mov_b64_e32 v[230:231], v[162:163]
	s_mov_b64 s[100:101], 0x1000
	v_lshl_add_u64 v[250:251], v[230:231], 0, s[100:101]
	global_load_dwordx4 v[180:183], v[230:231], off
	global_load_dwordx4 v[184:187], v[250:251], off
	global_load_dwordx4 v[188:191], v[230:231], off offset:256
	global_load_dwordx4 v[192:195], v[250:251], off offset:256
	s_mov_b64 s[100:101], 0x30000
	v_lshl_add_u64 v[248:249], v[230:231], 0, s[100:101]
	s_mov_b64 s[100:101], 0x1000
	v_lshl_add_u64 v[250:251], v[248:249], 0, s[100:101]
	global_load_dwordx4 v[196:199], v[248:249], off
	global_load_dwordx4 v[200:203], v[250:251], off
	global_load_dwordx4 v[204:207], v[248:249], off offset:256
	global_load_dwordx4 v[208:211], v[250:251], off offset:256
	s_mov_b64 s[100:101], 0x60000
	v_lshl_add_u64 v[248:249], v[230:231], 0, s[100:101]
	s_mov_b64 s[100:101], 0x1000
	v_lshl_add_u64 v[250:251], v[248:249], 0, s[100:101]
	global_load_dwordx4 v[232:235], v[248:249], off
	global_load_dwordx4 v[236:239], v[250:251], off
	global_load_dwordx4 v[240:243], v[248:249], off offset:256
	global_load_dwordx4 v[244:247], v[250:251], off offset:256
	s_nop 1
	s_cmp_lt_i32 s35, 2
	s_cselect_b64 s[28:29], -1, 0
	s_cmp_gt_i32 s35, 1
	s_cselect_b64 s[20:21], -1, 0
	s_add_i32 s24, s26, 0x800
	s_ashr_i32 s25, s24, 31
	s_and_b64 vcc, exec, s[20:21]
	v_lshl_add_u64 v[160:161], s[24:25], 1, v[130:131]
	s_waitcnt vmcnt(11)
	s_nop 1
	v_mov_b64_e32 v[168:169], v[180:181]
	v_mov_b64_e32 v[170:171], v[182:183]
	v_lshlrev_b32_e32 v166, 16, v168
	v_and_b32_e32 v167, 0xffff0000, v168
	v_lshlrev_b32_e32 v164, 16, v169
	v_and_b32_e32 v165, 0xffff0000, v169
	v_lshlrev_b32_e32 v168, 16, v170
	v_and_b32_e32 v169, 0xffff0000, v170
	v_lshlrev_b32_e32 v158, 16, v171
	v_and_b32_e32 v159, 0xffff0000, v171
	s_cbranch_vccnz .LBB0_1609
	v_lshl_add_u64 v[130:131], v[154:155], 1, v[160:161]
	s_nop 1
	s_waitcnt vmcnt(10)
	s_nop 1
	v_mov_b64_e32 v[176:177], v[184:185]
	v_mov_b64_e32 v[178:179], v[186:187]
	v_lshlrev_b32_e32 v130, 16, v176
	v_and_b32_e32 v131, 0xffff0000, v176
	v_max_f32_e32 v130, v130, v130
	v_max_f32_e32 v131, v131, v131
	v_max_f32_e32 v130, 0xda24260, v130
	v_max_f32_e32 v131, 0xda24260, v131
	v_rcp_f32_e32 v130, v130
	v_rcp_f32_e32 v131, v131
	v_lshlrev_b32_e32 v134, 16, v177
	v_and_b32_e32 v135, 0xffff0000, v177
	v_lshlrev_b32_e32 v140, 16, v178
	v_pk_mul_f32 v[166:167], v[130:131], v[166:167]
	v_max_f32_e32 v130, v134, v134
	v_max_f32_e32 v131, v135, v135
	v_max_f32_e32 v130, 0xda24260, v130
	v_max_f32_e32 v131, 0xda24260, v131
	v_rcp_f32_e32 v130, v130
	v_rcp_f32_e32 v131, v131
	v_and_b32_e32 v141, 0xffff0000, v178
	v_lshlrev_b32_e32 v142, 16, v179
	v_and_b32_e32 v143, 0xffff0000, v179
	v_pk_mul_f32 v[164:165], v[130:131], v[164:165]
	v_max_f32_e32 v130, v140, v140
	v_max_f32_e32 v131, v141, v141
	v_max_f32_e32 v130, 0xda24260, v130
	v_max_f32_e32 v131, 0xda24260, v131
	v_rcp_f32_e32 v130, v130
	v_rcp_f32_e32 v131, v131
	s_nop 0
	v_pk_mul_f32 v[168:169], v[130:131], v[168:169]
	v_max_f32_e32 v130, v142, v142
	v_max_f32_e32 v131, v143, v143
	v_max_f32_e32 v130, 0xda24260, v130
	v_max_f32_e32 v131, 0xda24260, v131
	v_rcp_f32_e32 v130, v130
	v_rcp_f32_e32 v131, v131
	s_nop 0
	v_pk_mul_f32 v[158:159], v[130:131], v[158:159]

;     __device__ __forceinline__ void operator()(f32x4 (&acc)[2][2][4][2], const Unit& u, int wr, int wc, int fr, int fq) const {
;     ...
;             for (int m = 0; m < 4; ++m) { const size_t row = (size_t)(row0 + ai * HALF + m * 16);
; #pragma unroll
;                 for (int bj = 0; bj < 2; ++bj) { const int col = col0 + bj * HALF;
;                     const u32x4 g = *(const u32x4*)(PG + row * 6144 + br * D + col);
;                     float s[8] = {bflo(g[0]), bfhi(g[0]), bflo(g[1]), bfhi(g[1]), bflo(g[2]), bfhi(g[2]), bflo(g[3]), bfhi(g[3])};
;                     if (br < 2) { const u32x4 h = *(const u32x4*)(PG + row * 6144 + (br + 1) * D + col);
;                         const float d[8] = {bflo(h[0]), bfhi(h[0]), bflo(h[1]), bfhi(h[1]), bflo(h[2]), bfhi(h[2]), bflo(h[3]), bfhi(h[3])};
; #pragma unroll
;                         for (int j = 0; j < 8; ++j) s[j] = s[j] * __builtin_amdgcn_rcpf(fmaxf(d[j], 1e-30f)); }
;                     f32x4& v0 = acc[ai][bj][m][0]; f32x4& v1 = acc[ai][bj][m][1];
; #pragma unroll
;                     for (int j = 0; j < 4; ++j) { v0[j] *= s[j]; v1[j] *= s[4 + j]; }
.LBB0_1611:
	s_nop 1
	v_cndmask_b32_e64 v130, 0, 1, s[28:29]
	v_cmp_ne_u32_e64 s[44:45], 1, v130
	s_andn2_b64 vcc, exec, s[28:29]
	s_waitcnt vmcnt(9)
	s_nop 1
	v_mov_b64_e32 v[168:169], v[188:189]
	v_mov_b64_e32 v[170:171], v[190:191]
	v_lshlrev_b32_e32 v166, 16, v168
	v_and_b32_e32 v167, 0xffff0000, v168
	v_lshlrev_b32_e32 v164, 16, v169
	v_and_b32_e32 v165, 0xffff0000, v169
	v_lshlrev_b32_e32 v168, 16, v170
	v_and_b32_e32 v169, 0xffff0000, v170
	v_lshlrev_b32_e32 v162, 16, v171
	v_and_b32_e32 v163, 0xffff0000, v171
	s_cbranch_vccnz .LBB0_1613
	v_lshl_add_u64 v[130:131], v[154:155], 1, v[160:161]
	s_nop 1
	s_waitcnt vmcnt(8)
	s_nop 1
	v_mov_b64_e32 v[176:177], v[192:193]
	v_mov_b64_e32 v[178:179], v[194:195]
	v_lshlrev_b32_e32 v130, 16, v176
	v_and_b32_e32 v131, 0xffff0000, v176
	v_max_f32_e32 v130, v130, v130
	v_max_f32_e32 v131, v131, v131
	v_max_f32_e32 v130, 0xda24260, v130
	v_max_f32_e32 v131, 0xda24260, v131
	v_rcp_f32_e32 v130, v130
	v_rcp_f32_e32 v131, v131
	v_lshlrev_b32_e32 v134, 16, v177
	v_and_b32_e32 v135, 0xffff0000, v177
	v_lshlrev_b32_e32 v140, 16, v178
	v_pk_mul_f32 v[166:167], v[130:131], v[166:167]
	v_max_f32_e32 v130, v134, v134
	v_max_f32_e32 v131, v135, v135
	v_max_f32_e32 v130, 0xda24260, v130
	v_max_f32_e32 v131, 0xda24260, v131
	v_rcp_f32_e32 v130, v130
	v_rcp_f32_e32 v131, v131
	v_and_b32_e32 v141, 0xffff0000, v178
	v_lshlrev_b32_e32 v142, 16, v179
	v_and_b32_e32 v143, 0xffff0000, v179
	v_pk_mul_f32 v[164:165], v[130:131], v[164:165]
	v_max_f32_e32 v130, v140, v140
	v_max_f32_e32 v131, v141, v141
	v_max_f32_e32 v130, 0xda24260, v130
	v_max_f32_e32 v131, 0xda24260, v131
	v_rcp_f32_e32 v130, v130
	v_rcp_f32_e32 v131, v131
	s_nop 0
	v_pk_mul_f32 v[168:169], v[130:131], v[168:169]
	v_max_f32_e32 v130, v142, v142
	v_max_f32_e32 v131, v143, v143
	v_max_f32_e32 v130, 0xda24260, v130
	v_max_f32_e32 v131, 0xda24260, v131
	v_rcp_f32_e32 v130, v130
	v_rcp_f32_e32 v131, v131
	s_nop 0
	v_pk_mul_f32 v[162:163], v[130:131], v[162:163]

;     __device__ __forceinline__ void operator()(f32x4 (&acc)[2][2][4][2], const Unit& u, int wr, int wc, int fr, int fq) const {
;     ...
;             for (int m = 0; m < 4; ++m) { const size_t row = (size_t)(row0 + ai * HALF + m * 16);
; #pragma unroll
;                 for (int bj = 0; bj < 2; ++bj) { const int col = col0 + bj * HALF;
;                     const u32x4 g = *(const u32x4*)(PG + row * 6144 + br * D + col);
;                     float s[8] = {bflo(g[0]), bfhi(g[0]), bflo(g[1]), bfhi(g[1]), bflo(g[2]), bfhi(g[2]), bflo(g[3]), bfhi(g[3])};
;                     if (br < 2) { const u32x4 h = *(const u32x4*)(PG + row * 6144 + (br + 1) * D + col);
;                         const float d[8] = {bflo(h[0]), bfhi(h[0]), bflo(h[1]), bfhi(h[1]), bflo(h[2]), bfhi(h[2]), bflo(h[3]), bfhi(h[3])};
; #pragma unroll
;                         for (int j = 0; j < 8; ++j) s[j] = s[j] * __builtin_amdgcn_rcpf(fmaxf(d[j], 1e-30f)); }
;                     f32x4& v0 = acc[ai][bj][m][0]; f32x4& v1 = acc[ai][bj][m][1];
; #pragma unroll
;                     for (int j = 0; j < 4; ++j) { v0[j] *= s[j]; v1[j] *= s[4 + j]; }
.LBB0_1615:
	v_or_b32_e32 v158, 16, v156
	v_mov_b64_e32 v[130:131], s[6:7]
	v_mad_i64_i32 v[130:131], s[2:3], v158, s13, v[130:131]
	v_lshl_add_u64 v[134:135], s[26:27], 1, v[130:131]
	v_lshl_add_u64 v[162:163], v[154:155], 1, v[134:135]
	s_mov_b64 s[100:101], 0x90000
	v_lshl_add_u64 v[248:249], v[230:231], 0, s[100:101]
	s_mov_b64 s[100:101], 0x1000
	v_lshl_add_u64 v[250:251], v[248:249], 0, s[100:101]
	global_load_dwordx4 v[180:183], v[248:249], off
	global_load_dwordx4 v[184:187], v[250:251], off
	global_load_dwordx4 v[188:191], v[248:249], off offset:256
	global_load_dwordx4 v[192:195], v[250:251], off offset:256
	s_nop 1
	s_and_b64 vcc, exec, s[44:45]
	v_lshl_add_u64 v[160:161], s[24:25], 1, v[130:131]
	s_waitcnt vmcnt(11)
	s_nop 1
	v_mov_b64_e32 v[176:177], v[196:197]
	v_mov_b64_e32 v[178:179], v[198:199]
	v_lshlrev_b32_e32 v168, 16, v176
	v_and_b32_e32 v169, 0xffff0000, v176
	v_lshlrev_b32_e32 v166, 16, v177
	v_and_b32_e32 v167, 0xffff0000, v177
	v_lshlrev_b32_e32 v170, 16, v178
	v_and_b32_e32 v171, 0xffff0000, v178
	v_lshlrev_b32_e32 v164, 16, v179
	v_and_b32_e32 v165, 0xffff0000, v179
	s_cbranch_vccnz .LBB0_1617
	v_lshl_add_u64 v[130:131], v[154:155], 1, v[160:161]
	s_nop 1
	s_waitcnt vmcnt(10)
	s_nop 1
	v_mov_b64_e32 v[176:177], v[200:201]
	v_mov_b64_e32 v[178:179], v[202:203]
	v_lshlrev_b32_e32 v130, 16, v176
	v_and_b32_e32 v131, 0xffff0000, v176
	v_max_f32_e32 v130, v130, v130
	v_max_f32_e32 v131, v131, v131
	v_max_f32_e32 v130, 0xda24260, v130
	v_max_f32_e32 v131, 0xda24260, v131
	v_rcp_f32_e32 v130, v130
	v_rcp_f32_e32 v131, v131
	v_lshlrev_b32_e32 v134, 16, v177
	v_and_b32_e32 v135, 0xffff0000, v177
	v_lshlrev_b32_e32 v140, 16, v178
	v_pk_mul_f32 v[168:169], v[130:131], v[168:169]
	v_max_f32_e32 v130, v134, v134
	v_max_f32_e32 v131, v135, v135
	v_max_f32_e32 v130, 0xda24260, v130
	v_max_f32_e32 v131, 0xda24260, v131
	v_rcp_f32_e32 v130, v130
	v_rcp_f32_e32 v131, v131
	v_and_b32_e32 v141, 0xffff0000, v178
	v_lshlrev_b32_e32 v142, 16, v179
	v_and_b32_e32 v143, 0xffff0000, v179
	v_pk_mul_f32 v[166:167], v[130:131], v[166:167]
	v_max_f32_e32 v130, v140, v140
	v_max_f32_e32 v131, v141, v141
	v_max_f32_e32 v130, 0xda24260, v130
	v_max_f32_e32 v131, 0xda24260, v131
	v_rcp_f32_e32 v130, v130
	v_rcp_f32_e32 v131, v131
	s_nop 0
	v_pk_mul_f32 v[170:171], v[130:131], v[170:171]
	v_max_f32_e32 v130, v142, v142
	v_max_f32_e32 v131, v143, v143
	v_max_f32_e32 v130, 0xda24260, v130
	v_max_f32_e32 v131, 0xda24260, v131
	v_rcp_f32_e32 v130, v130
	v_rcp_f32_e32 v131, v131
	s_nop 0
	v_pk_mul_f32 v[164:165], v[130:131], v[164:165]

;     __device__ __forceinline__ void operator()(f32x4 (&acc)[2][2][4][2], const Unit& u, int wr, int wc, int fr, int fq) const {
;     ...
;             for (int m = 0; m < 4; ++m) { const size_t row = (size_t)(row0 + ai * HALF + m * 16);
; #pragma unroll
;                 for (int bj = 0; bj < 2; ++bj) { const int col = col0 + bj * HALF;
;                     const u32x4 g = *(const u32x4*)(PG + row * 6144 + br * D + col);
;                     float s[8] = {bflo(g[0]), bfhi(g[0]), bflo(g[1]), bfhi(g[1]), bflo(g[2]), bfhi(g[2]), bflo(g[3]), bfhi(g[3])};
;                     if (br < 2) { const u32x4 h = *(const u32x4*)(PG + row * 6144 + (br + 1) * D + col);
;                         const float d[8] = {bflo(h[0]), bfhi(h[0]), bflo(h[1]), bfhi(h[1]), bflo(h[2]), bfhi(h[2]), bflo(h[3]), bfhi(h[3])};
; #pragma unroll
;                         for (int j = 0; j < 8; ++j) s[j] = s[j] * __builtin_amdgcn_rcpf(fmaxf(d[j], 1e-30f)); }
;                     f32x4& v0 = acc[ai][bj][m][0]; f32x4& v1 = acc[ai][bj][m][1];
; #pragma unroll
;                     for (int j = 0; j < 4; ++j) { v0[j] *= s[j]; v1[j] *= s[4 + j]; }
.LBB0_1619:
	s_nop 1
	s_and_b64 vcc, exec, s[44:45]
	s_waitcnt vmcnt(9)
	s_nop 1
	v_mov_b64_e32 v[168:169], v[204:205]
	v_mov_b64_e32 v[170:171], v[206:207]
	v_lshlrev_b32_e32 v166, 16, v168
	v_and_b32_e32 v167, 0xffff0000, v168
	v_lshlrev_b32_e32 v164, 16, v169
	v_and_b32_e32 v165, 0xffff0000, v169
	v_lshlrev_b32_e32 v168, 16, v170
	v_and_b32_e32 v169, 0xffff0000, v170
	v_lshlrev_b32_e32 v162, 16, v171
	v_and_b32_e32 v163, 0xffff0000, v171
	s_cbranch_vccnz .LBB0_1621
	v_lshl_add_u64 v[130:131], v[154:155], 1, v[160:161]
	s_nop 1
	s_waitcnt vmcnt(8)
	s_nop 1
	v_mov_b64_e32 v[176:177], v[208:209]
	v_mov_b64_e32 v[178:179], v[210:211]
	v_lshlrev_b32_e32 v130, 16, v176
	v_and_b32_e32 v131, 0xffff0000, v176
	v_max_f32_e32 v130, v130, v130
	v_max_f32_e32 v131, v131, v131
	v_max_f32_e32 v130, 0xda24260, v130
	v_max_f32_e32 v131, 0xda24260, v131
	v_rcp_f32_e32 v130, v130
	v_rcp_f32_e32 v131, v131
	v_lshlrev_b32_e32 v134, 16, v177
	v_and_b32_e32 v135, 0xffff0000, v177
	v_lshlrev_b32_e32 v140, 16, v178
	v_pk_mul_f32 v[166:167], v[130:131], v[166:167]
	v_max_f32_e32 v130, v134, v134
	v_max_f32_e32 v131, v135, v135
	v_max_f32_e32 v130, 0xda24260, v130
	v_max_f32_e32 v131, 0xda24260, v131
	v_rcp_f32_e32 v130, v130
	v_rcp_f32_e32 v131, v131
	v_and_b32_e32 v141, 0xffff0000, v178
	v_lshlrev_b32_e32 v142, 16, v179
	v_and_b32_e32 v143, 0xffff0000, v179
	v_pk_mul_f32 v[164:165], v[130:131], v[164:165]
	v_max_f32_e32 v130, v140, v140
	v_max_f32_e32 v131, v141, v141
	v_max_f32_e32 v130, 0xda24260, v130
	v_max_f32_e32 v131, 0xda24260, v131
	v_rcp_f32_e32 v130, v130
	v_rcp_f32_e32 v131, v131
	s_nop 0
	v_pk_mul_f32 v[168:169], v[130:131], v[168:169]
	v_max_f32_e32 v130, v142, v142
	v_max_f32_e32 v131, v143, v143
	v_max_f32_e32 v130, 0xda24260, v130
	v_max_f32_e32 v131, 0xda24260, v131
	v_rcp_f32_e32 v130, v130
	v_rcp_f32_e32 v131, v131
	s_nop 0
	v_pk_mul_f32 v[162:163], v[130:131], v[162:163]

;     __device__ __forceinline__ void operator()(f32x4 (&acc)[2][2][4][2], const Unit& u, int wr, int wc, int fr, int fq) const {
;     ...
;             for (int m = 0; m < 4; ++m) { const size_t row = (size_t)(row0 + ai * HALF + m * 16);
; #pragma unroll
;                 for (int bj = 0; bj < 2; ++bj) { const int col = col0 + bj * HALF;
;                     const u32x4 g = *(const u32x4*)(PG + row * 6144 + br * D + col);
;                     float s[8] = {bflo(g[0]), bfhi(g[0]), bflo(g[1]), bfhi(g[1]), bflo(g[2]), bfhi(g[2]), bflo(g[3]), bfhi(g[3])};
;                     if (br < 2) { const u32x4 h = *(const u32x4*)(PG + row * 6144 + (br + 1) * D + col);
;                         const float d[8] = {bflo(h[0]), bfhi(h[0]), bflo(h[1]), bfhi(h[1]), bflo(h[2]), bfhi(h[2]), bflo(h[3]), bfhi(h[3])};
; #pragma unroll
;                         for (int j = 0; j < 8; ++j) s[j] = s[j] * __builtin_amdgcn_rcpf(fmaxf(d[j], 1e-30f)); }
;                     f32x4& v0 = acc[ai][bj][m][0]; f32x4& v1 = acc[ai][bj][m][1];
; #pragma unroll
;                     for (int j = 0; j < 4; ++j) { v0[j] *= s[j]; v1[j] *= s[4 + j]; }
.LBB0_1623:
	v_or_b32_e32 v158, 32, v156
	v_mov_b64_e32 v[130:131], s[6:7]
	v_mad_i64_i32 v[130:131], s[2:3], v158, s13, v[130:131]
	v_lshl_add_u64 v[134:135], s[26:27], 1, v[130:131]
	v_lshl_add_u64 v[162:163], v[154:155], 1, v[134:135]
	s_mov_b64 s[100:101], 0x180000
	v_lshl_add_u64 v[248:249], v[230:231], 0, s[100:101]
	s_mov_b64 s[100:101], 0x1000
	v_lshl_add_u64 v[250:251], v[248:249], 0, s[100:101]
	global_load_dwordx4 v[196:199], v[248:249], off
	global_load_dwordx4 v[200:203], v[250:251], off
	global_load_dwordx4 v[204:207], v[248:249], off offset:256
	global_load_dwordx4 v[208:211], v[250:251], off offset:256
	s_nop 1
	s_and_b64 vcc, exec, s[44:45]
	v_lshl_add_u64 v[160:161], s[24:25], 1, v[130:131]
	s_waitcnt vmcnt(11)
	s_nop 1
	v_mov_b64_e32 v[176:177], v[232:233]
	v_mov_b64_e32 v[178:179], v[234:235]
	v_lshlrev_b32_e32 v168, 16, v176
	v_and_b32_e32 v169, 0xffff0000, v176
	v_lshlrev_b32_e32 v166, 16, v177
	v_and_b32_e32 v167, 0xffff0000, v177
	v_lshlrev_b32_e32 v170, 16, v178
	v_and_b32_e32 v171, 0xffff0000, v178
	v_lshlrev_b32_e32 v164, 16, v179
	v_and_b32_e32 v165, 0xffff0000, v179
	s_cbranch_vccnz .LBB0_1625
	v_lshl_add_u64 v[130:131], v[154:155], 1, v[160:161]
	s_nop 1
	s_waitcnt vmcnt(10)
	s_nop 1
	v_mov_b64_e32 v[176:177], v[236:237]
	v_mov_b64_e32 v[178:179], v[238:239]
	v_lshlrev_b32_e32 v130, 16, v176
	v_and_b32_e32 v131, 0xffff0000, v176
	v_max_f32_e32 v130, v130, v130
	v_max_f32_e32 v131, v131, v131
	v_max_f32_e32 v130, 0xda24260, v130
	v_max_f32_e32 v131, 0xda24260, v131
	v_rcp_f32_e32 v130, v130
	v_rcp_f32_e32 v131, v131
	v_lshlrev_b32_e32 v134, 16, v177
	v_and_b32_e32 v135, 0xffff0000, v177
	v_lshlrev_b32_e32 v140, 16, v178
	v_pk_mul_f32 v[168:169], v[130:131], v[168:169]
	v_max_f32_e32 v130, v134, v134
	v_max_f32_e32 v131, v135, v135
	v_max_f32_e32 v130, 0xda24260, v130
	v_max_f32_e32 v131, 0xda24260, v131
	v_rcp_f32_e32 v130, v130
	v_rcp_f32_e32 v131, v131
	v_and_b32_e32 v141, 0xffff0000, v178
	v_lshlrev_b32_e32 v142, 16, v179
	v_and_b32_e32 v143, 0xffff0000, v179
	v_pk_mul_f32 v[166:167], v[130:131], v[166:167]
	v_max_f32_e32 v130, v140, v140
	v_max_f32_e32 v131, v141, v141
	v_max_f32_e32 v130, 0xda24260, v130
	v_max_f32_e32 v131, 0xda24260, v131
	v_rcp_f32_e32 v130, v130
	v_rcp_f32_e32 v131, v131
	s_nop 0
	v_pk_mul_f32 v[170:171], v[130:131], v[170:171]
	v_max_f32_e32 v130, v142, v142
	v_max_f32_e32 v131, v143, v143
	v_max_f32_e32 v130, 0xda24260, v130
	v_max_f32_e32 v131, 0xda24260, v131
	v_rcp_f32_e32 v130, v130
	v_rcp_f32_e32 v131, v131
	s_nop 0
	v_pk_mul_f32 v[164:165], v[130:131], v[164:165]

;     __device__ __forceinline__ void operator()(f32x4 (&acc)[2][2][4][2], const Unit& u, int wr, int wc, int fr, int fq) const {
;     ...
;             for (int m = 0; m < 4; ++m) { const size_t row = (size_t)(row0 + ai * HALF + m * 16);
; #pragma unroll
;                 for (int bj = 0; bj < 2; ++bj) { const int col = col0 + bj * HALF;
;                     const u32x4 g = *(const u32x4*)(PG + row * 6144 + br * D + col);
;                     float s[8] = {bflo(g[0]), bfhi(g[0]), bflo(g[1]), bfhi(g[1]), bflo(g[2]), bfhi(g[2]), bflo(g[3]), bfhi(g[3])};
;                     if (br < 2) { const u32x4 h = *(const u32x4*)(PG + row * 6144 + (br + 1) * D + col);
;                         const float d[8] = {bflo(h[0]), bfhi(h[0]), bflo(h[1]), bfhi(h[1]), bflo(h[2]), bfhi(h[2]), bflo(h[3]), bfhi(h[3])};
; #pragma unroll
;                         for (int j = 0; j < 8; ++j) s[j] = s[j] * __builtin_amdgcn_rcpf(fmaxf(d[j], 1e-30f)); }
;                     f32x4& v0 = acc[ai][bj][m][0]; f32x4& v1 = acc[ai][bj][m][1];
; #pragma unroll
;                     for (int j = 0; j < 4; ++j) { v0[j] *= s[j]; v1[j] *= s[4 + j]; }
.LBB0_1627:
	s_nop 1
	s_and_b64 vcc, exec, s[44:45]
	s_waitcnt vmcnt(9)
	s_nop 1
	v_mov_b64_e32 v[168:169], v[240:241]
	v_mov_b64_e32 v[170:171], v[242:243]
	v_lshlrev_b32_e32 v166, 16, v168
	v_and_b32_e32 v167, 0xffff0000, v168
	v_lshlrev_b32_e32 v164, 16, v169
	v_and_b32_e32 v165, 0xffff0000, v169
	v_lshlrev_b32_e32 v168, 16, v170
	v_and_b32_e32 v169, 0xffff0000, v170
	v_lshlrev_b32_e32 v162, 16, v171
	v_and_b32_e32 v163, 0xffff0000, v171
	s_cbranch_vccnz .LBB0_1629
	v_lshl_add_u64 v[130:131], v[154:155], 1, v[160:161]
	s_nop 1
	s_waitcnt vmcnt(8)
	s_nop 1
	v_mov_b64_e32 v[176:177], v[244:245]
	v_mov_b64_e32 v[178:179], v[246:247]
	v_lshlrev_b32_e32 v130, 16, v176
	v_and_b32_e32 v131, 0xffff0000, v176
	v_max_f32_e32 v130, v130, v130
	v_max_f32_e32 v131, v131, v131
	v_max_f32_e32 v130, 0xda24260, v130
	v_max_f32_e32 v131, 0xda24260, v131
	v_rcp_f32_e32 v130, v130
	v_rcp_f32_e32 v131, v131
	v_lshlrev_b32_e32 v134, 16, v177
	v_and_b32_e32 v135, 0xffff0000, v177
	v_lshlrev_b32_e32 v140, 16, v178
	v_pk_mul_f32 v[166:167], v[130:131], v[166:167]
	v_max_f32_e32 v130, v134, v134
	v_max_f32_e32 v131, v135, v135
	v_max_f32_e32 v130, 0xda24260, v130
	v_max_f32_e32 v131, 0xda24260, v131
	v_rcp_f32_e32 v130, v130
	v_rcp_f32_e32 v131, v131
	v_and_b32_e32 v141, 0xffff0000, v178
	v_lshlrev_b32_e32 v142, 16, v179
	v_and_b32_e32 v143, 0xffff0000, v179
	v_pk_mul_f32 v[164:165], v[130:131], v[164:165]
	v_max_f32_e32 v130, v140, v140
	v_max_f32_e32 v131, v141, v141
	v_max_f32_e32 v130, 0xda24260, v130
	v_max_f32_e32 v131, 0xda24260, v131
	v_rcp_f32_e32 v130, v130
	v_rcp_f32_e32 v131, v131
	s_nop 0
	v_pk_mul_f32 v[168:169], v[130:131], v[168:169]
	v_max_f32_e32 v130, v142, v142
	v_max_f32_e32 v131, v143, v143
	v_max_f32_e32 v130, 0xda24260, v130
	v_max_f32_e32 v131, 0xda24260, v131
	v_rcp_f32_e32 v130, v130
	v_rcp_f32_e32 v131, v131
	s_nop 0
	v_pk_mul_f32 v[162:163], v[130:131], v[162:163]

;     __device__ __forceinline__ void operator()(f32x4 (&acc)[2][2][4][2], const Unit& u, int wr, int wc, int fr, int fq) const {
;     ...
;             for (int m = 0; m < 4; ++m) { const size_t row = (size_t)(row0 + ai * HALF + m * 16);
; #pragma unroll
;                 for (int bj = 0; bj < 2; ++bj) { const int col = col0 + bj * HALF;
;                     const u32x4 g = *(const u32x4*)(PG + row * 6144 + br * D + col);
;                     float s[8] = {bflo(g[0]), bfhi(g[0]), bflo(g[1]), bfhi(g[1]), bflo(g[2]), bfhi(g[2]), bflo(g[3]), bfhi(g[3])};
;                     if (br < 2) { const u32x4 h = *(const u32x4*)(PG + row * 6144 + (br + 1) * D + col);
;                         const float d[8] = {bflo(h[0]), bfhi(h[0]), bflo(h[1]), bfhi(h[1]), bflo(h[2]), bfhi(h[2]), bflo(h[3]), bfhi(h[3])};
; #pragma unroll
;                         for (int j = 0; j < 8; ++j) s[j] = s[j] * __builtin_amdgcn_rcpf(fmaxf(d[j], 1e-30f)); }
;                     f32x4& v0 = acc[ai][bj][m][0]; f32x4& v1 = acc[ai][bj][m][1];
; #pragma unroll
;                     for (int j = 0; j < 4; ++j) { v0[j] *= s[j]; v1[j] *= s[4 + j]; }
.LBB0_1631:
	v_or_b32_e32 v158, 48, v156
	v_mov_b64_e32 v[130:131], s[6:7]
	v_mad_i64_i32 v[130:131], s[2:3], v158, s13, v[130:131]
	v_lshl_add_u64 v[134:135], s[26:27], 1, v[130:131]
	v_lshl_add_u64 v[162:163], v[154:155], 1, v[134:135]
	s_mov_b64 s[100:101], 0x1b0000
	v_lshl_add_u64 v[248:249], v[230:231], 0, s[100:101]
	s_mov_b64 s[100:101], 0x1000
	v_lshl_add_u64 v[250:251], v[248:249], 0, s[100:101]
	global_load_dwordx4 v[232:235], v[248:249], off
	global_load_dwordx4 v[236:239], v[250:251], off
	global_load_dwordx4 v[240:243], v[248:249], off offset:256
	global_load_dwordx4 v[244:247], v[250:251], off offset:256
	s_nop 1
	s_and_b64 vcc, exec, s[44:45]
	v_lshl_add_u64 v[160:161], s[24:25], 1, v[130:131]
	s_waitcnt vmcnt(11)
	s_nop 1
	v_mov_b64_e32 v[176:177], v[180:181]
	v_mov_b64_e32 v[178:179], v[182:183]
	v_lshlrev_b32_e32 v168, 16, v176
	v_and_b32_e32 v169, 0xffff0000, v176
	v_lshlrev_b32_e32 v166, 16, v177
	v_and_b32_e32 v167, 0xffff0000, v177
	v_lshlrev_b32_e32 v170, 16, v178
	v_and_b32_e32 v171, 0xffff0000, v178
	v_lshlrev_b32_e32 v164, 16, v179
	v_and_b32_e32 v165, 0xffff0000, v179
	s_cbranch_vccnz .LBB0_1633
	v_lshl_add_u64 v[130:131], v[154:155], 1, v[160:161]
	s_nop 1
	s_waitcnt vmcnt(10)
	s_nop 1
	v_mov_b64_e32 v[176:177], v[184:185]
	v_mov_b64_e32 v[178:179], v[186:187]
	v_lshlrev_b32_e32 v130, 16, v176
	v_and_b32_e32 v131, 0xffff0000, v176
	v_max_f32_e32 v130, v130, v130
	v_max_f32_e32 v131, v131, v131
	v_max_f32_e32 v130, 0xda24260, v130
	v_max_f32_e32 v131, 0xda24260, v131
	v_rcp_f32_e32 v130, v130
	v_rcp_f32_e32 v131, v131
	v_lshlrev_b32_e32 v134, 16, v177
	v_and_b32_e32 v135, 0xffff0000, v177
	v_lshlrev_b32_e32 v140, 16, v178
	v_pk_mul_f32 v[168:169], v[130:131], v[168:169]
	v_max_f32_e32 v130, v134, v134
	v_max_f32_e32 v131, v135, v135
	v_max_f32_e32 v130, 0xda24260, v130
	v_max_f32_e32 v131, 0xda24260, v131
	v_rcp_f32_e32 v130, v130
	v_rcp_f32_e32 v131, v131
	v_and_b32_e32 v141, 0xffff0000, v178
	v_lshlrev_b32_e32 v142, 16, v179
	v_and_b32_e32 v143, 0xffff0000, v179
	v_pk_mul_f32 v[166:167], v[130:131], v[166:167]
	v_max_f32_e32 v130, v140, v140
	v_max_f32_e32 v131, v141, v141
	v_max_f32_e32 v130, 0xda24260, v130
	v_max_f32_e32 v131, 0xda24260, v131
	v_rcp_f32_e32 v130, v130
	v_rcp_f32_e32 v131, v131
	s_nop 0
	v_pk_mul_f32 v[170:171], v[130:131], v[170:171]
	v_max_f32_e32 v130, v142, v142
	v_max_f32_e32 v131, v143, v143
	v_max_f32_e32 v130, 0xda24260, v130
	v_max_f32_e32 v131, 0xda24260, v131
	v_rcp_f32_e32 v130, v130
	v_rcp_f32_e32 v131, v131
	s_nop 0
	v_pk_mul_f32 v[164:165], v[130:131], v[164:165]

;     __device__ __forceinline__ void operator()(f32x4 (&acc)[2][2][4][2], const Unit& u, int wr, int wc, int fr, int fq) const {
;     ...
;             for (int m = 0; m < 4; ++m) { const size_t row = (size_t)(row0 + ai * HALF + m * 16);
; #pragma unroll
;                 for (int bj = 0; bj < 2; ++bj) { const int col = col0 + bj * HALF;
;                     const u32x4 g = *(const u32x4*)(PG + row * 6144 + br * D + col);
;                     float s[8] = {bflo(g[0]), bfhi(g[0]), bflo(g[1]), bfhi(g[1]), bflo(g[2]), bfhi(g[2]), bflo(g[3]), bfhi(g[3])};
;                     if (br < 2) { const u32x4 h = *(const u32x4*)(PG + row * 6144 + (br + 1) * D + col);
;                         const float d[8] = {bflo(h[0]), bfhi(h[0]), bflo(h[1]), bfhi(h[1]), bflo(h[2]), bfhi(h[2]), bflo(h[3]), bfhi(h[3])};
; #pragma unroll
;                         for (int j = 0; j < 8; ++j) s[j] = s[j] * __builtin_amdgcn_rcpf(fmaxf(d[j], 1e-30f)); }
;                     f32x4& v0 = acc[ai][bj][m][0]; f32x4& v1 = acc[ai][bj][m][1];
; #pragma unroll
;                     for (int j = 0; j < 4; ++j) { v0[j] *= s[j]; v1[j] *= s[4 + j]; }
.LBB0_1635:
	s_nop 1
	s_and_b64 vcc, exec, s[44:45]
	s_waitcnt vmcnt(9)
	s_nop 1
	v_mov_b64_e32 v[168:169], v[188:189]
	v_mov_b64_e32 v[170:171], v[190:191]
	v_lshlrev_b32_e32 v166, 16, v168
	v_and_b32_e32 v167, 0xffff0000, v168
	v_lshlrev_b32_e32 v164, 16, v169
	v_and_b32_e32 v165, 0xffff0000, v169
	v_lshlrev_b32_e32 v168, 16, v170
	v_and_b32_e32 v169, 0xffff0000, v170
	v_lshlrev_b32_e32 v162, 16, v171
	v_and_b32_e32 v163, 0xffff0000, v171
	s_cbranch_vccnz .LBB0_1637
	v_lshl_add_u64 v[130:131], v[154:155], 1, v[160:161]
	s_nop 1
	s_waitcnt vmcnt(8)
	s_nop 1
	v_mov_b64_e32 v[176:177], v[192:193]
	v_mov_b64_e32 v[178:179], v[194:195]
	v_lshlrev_b32_e32 v130, 16, v176
	v_and_b32_e32 v131, 0xffff0000, v176
	v_max_f32_e32 v130, v130, v130
	v_max_f32_e32 v131, v131, v131
	v_max_f32_e32 v130, 0xda24260, v130
	v_max_f32_e32 v131, 0xda24260, v131
	v_rcp_f32_e32 v130, v130
	v_rcp_f32_e32 v131, v131
	v_lshlrev_b32_e32 v134, 16, v177
	v_and_b32_e32 v135, 0xffff0000, v177
	v_lshlrev_b32_e32 v140, 16, v178
	v_pk_mul_f32 v[166:167], v[130:131], v[166:167]
	v_max_f32_e32 v130, v134, v134
	v_max_f32_e32 v131, v135, v135
	v_max_f32_e32 v130, 0xda24260, v130
	v_max_f32_e32 v131, 0xda24260, v131
	v_rcp_f32_e32 v130, v130
	v_rcp_f32_e32 v131, v131
	v_and_b32_e32 v141, 0xffff0000, v178
	v_lshlrev_b32_e32 v142, 16, v179
	v_and_b32_e32 v143, 0xffff0000, v179
	v_pk_mul_f32 v[164:165], v[130:131], v[164:165]
	v_max_f32_e32 v130, v140, v140
	v_max_f32_e32 v131, v141, v141
	v_max_f32_e32 v130, 0xda24260, v130
	v_max_f32_e32 v131, 0xda24260, v131
	v_rcp_f32_e32 v130, v130
	v_rcp_f32_e32 v131, v131
	s_nop 0
	v_pk_mul_f32 v[168:169], v[130:131], v[168:169]
	v_max_f32_e32 v130, v142, v142
	v_max_f32_e32 v131, v143, v143
	v_max_f32_e32 v130, 0xda24260, v130
	v_max_f32_e32 v131, 0xda24260, v131
	v_rcp_f32_e32 v130, v130
	v_rcp_f32_e32 v131, v131
	s_nop 0
	v_pk_mul_f32 v[162:163], v[130:131], v[162:163]

;     __device__ __forceinline__ void operator()(f32x4 (&acc)[2][2][4][2], const Unit& u, int wr, int wc, int fr, int fq) const {
;     ...
;             for (int m = 0; m < 4; ++m) { const size_t row = (size_t)(row0 + ai * HALF + m * 16);
; #pragma unroll
;                 for (int bj = 0; bj < 2; ++bj) { const int col = col0 + bj * HALF;
;                     const u32x4 g = *(const u32x4*)(PG + row * 6144 + br * D + col);
;                     float s[8] = {bflo(g[0]), bfhi(g[0]), bflo(g[1]), bfhi(g[1]), bflo(g[2]), bfhi(g[2]), bflo(g[3]), bfhi(g[3])};
;                     if (br < 2) { const u32x4 h = *(const u32x4*)(PG + row * 6144 + (br + 1) * D + col);
;                         const float d[8] = {bflo(h[0]), bfhi(h[0]), bflo(h[1]), bfhi(h[1]), bflo(h[2]), bfhi(h[2]), bflo(h[3]), bfhi(h[3])};
; #pragma unroll
;                         for (int j = 0; j < 8; ++j) s[j] = s[j] * __builtin_amdgcn_rcpf(fmaxf(d[j], 1e-30f)); }
;                     f32x4& v0 = acc[ai][bj][m][0]; f32x4& v1 = acc[ai][bj][m][1];
; #pragma unroll
;                     for (int j = 0; j < 4; ++j) { v0[j] *= s[j]; v1[j] *= s[4 + j]; }
.LBB0_1639:
	v_add_u32_e32 v158, 0x80, v156
	v_mov_b64_e32 v[130:131], s[6:7]
	v_mad_i64_i32 v[130:131], s[2:3], v158, s13, v[130:131]
	v_lshl_add_u64 v[134:135], s[26:27], 1, v[130:131]
	v_lshl_add_u64 v[162:163], v[154:155], 1, v[134:135]
	s_mov_b64 s[100:101], 0x1e0000
	v_lshl_add_u64 v[248:249], v[230:231], 0, s[100:101]
	s_mov_b64 s[100:101], 0x1000
	v_lshl_add_u64 v[250:251], v[248:249], 0, s[100:101]
	global_load_dwordx4 v[180:183], v[248:249], off
	global_load_dwordx4 v[184:187], v[250:251], off
	global_load_dwordx4 v[188:191], v[248:249], off offset:256
	global_load_dwordx4 v[192:195], v[250:251], off offset:256
	s_nop 1
	s_and_b64 vcc, exec, s[44:45]
	v_lshl_add_u64 v[160:161], s[24:25], 1, v[130:131]
	s_waitcnt vmcnt(11)
	s_nop 1
	v_mov_b64_e32 v[176:177], v[196:197]
	v_mov_b64_e32 v[178:179], v[198:199]
	v_lshlrev_b32_e32 v168, 16, v176
	v_and_b32_e32 v169, 0xffff0000, v176
	v_lshlrev_b32_e32 v166, 16, v177
	v_and_b32_e32 v167, 0xffff0000, v177
	v_lshlrev_b32_e32 v170, 16, v178
	v_and_b32_e32 v171, 0xffff0000, v178
	v_lshlrev_b32_e32 v164, 16, v179
	v_and_b32_e32 v165, 0xffff0000, v179
	s_cbranch_vccnz .LBB0_1641
	v_lshl_add_u64 v[130:131], v[154:155], 1, v[160:161]
	s_nop 1
	s_waitcnt vmcnt(10)
	s_nop 1
	v_mov_b64_e32 v[176:177], v[200:201]
	v_mov_b64_e32 v[178:179], v[202:203]
	v_lshlrev_b32_e32 v130, 16, v176
	v_and_b32_e32 v131, 0xffff0000, v176
	v_max_f32_e32 v130, v130, v130
	v_max_f32_e32 v131, v131, v131
	v_max_f32_e32 v130, 0xda24260, v130
	v_max_f32_e32 v131, 0xda24260, v131
	v_rcp_f32_e32 v130, v130
	v_rcp_f32_e32 v131, v131
	v_lshlrev_b32_e32 v134, 16, v177
	v_and_b32_e32 v135, 0xffff0000, v177
	v_lshlrev_b32_e32 v140, 16, v178
	v_pk_mul_f32 v[168:169], v[130:131], v[168:169]
	v_max_f32_e32 v130, v134, v134
	v_max_f32_e32 v131, v135, v135
	v_max_f32_e32 v130, 0xda24260, v130
	v_max_f32_e32 v131, 0xda24260, v131
	v_rcp_f32_e32 v130, v130
	v_rcp_f32_e32 v131, v131
	v_and_b32_e32 v141, 0xffff0000, v178
	v_lshlrev_b32_e32 v142, 16, v179
	v_and_b32_e32 v143, 0xffff0000, v179
	v_pk_mul_f32 v[166:167], v[130:131], v[166:167]
	v_max_f32_e32 v130, v140, v140
	v_max_f32_e32 v131, v141, v141
	v_max_f32_e32 v130, 0xda24260, v130
	v_max_f32_e32 v131, 0xda24260, v131
	v_rcp_f32_e32 v130, v130
	v_rcp_f32_e32 v131, v131
	s_nop 0
	v_pk_mul_f32 v[170:171], v[130:131], v[170:171]
	v_max_f32_e32 v130, v142, v142
	v_max_f32_e32 v131, v143, v143
	v_max_f32_e32 v130, 0xda24260, v130
	v_max_f32_e32 v131, 0xda24260, v131
	v_rcp_f32_e32 v130, v130
	v_rcp_f32_e32 v131, v131
	s_nop 0
	v_pk_mul_f32 v[164:165], v[130:131], v[164:165]

;     __device__ __forceinline__ void operator()(f32x4 (&acc)[2][2][4][2], const Unit& u, int wr, int wc, int fr, int fq) const {
;     ...
;             for (int m = 0; m < 4; ++m) { const size_t row = (size_t)(row0 + ai * HALF + m * 16);
; #pragma unroll
;                 for (int bj = 0; bj < 2; ++bj) { const int col = col0 + bj * HALF;
;                     const u32x4 g = *(const u32x4*)(PG + row * 6144 + br * D + col);
;                     float s[8] = {bflo(g[0]), bfhi(g[0]), bflo(g[1]), bfhi(g[1]), bflo(g[2]), bfhi(g[2]), bflo(g[3]), bfhi(g[3])};
;                     if (br < 2) { const u32x4 h = *(const u32x4*)(PG + row * 6144 + (br + 1) * D + col);
;                         const float d[8] = {bflo(h[0]), bfhi(h[0]), bflo(h[1]), bfhi(h[1]), bflo(h[2]), bfhi(h[2]), bflo(h[3]), bfhi(h[3])};
; #pragma unroll
;                         for (int j = 0; j < 8; ++j) s[j] = s[j] * __builtin_amdgcn_rcpf(fmaxf(d[j], 1e-30f)); }
;                     f32x4& v0 = acc[ai][bj][m][0]; f32x4& v1 = acc[ai][bj][m][1];
; #pragma unroll
;                     for (int j = 0; j < 4; ++j) { v0[j] *= s[j]; v1[j] *= s[4 + j]; }
.LBB0_1647:
	v_add_u32_e32 v158, 0x90, v156
	v_mov_b64_e32 v[130:131], s[6:7]
	v_mad_i64_i32 v[130:131], s[2:3], v158, s13, v[130:131]
	v_lshl_add_u64 v[134:135], s[26:27], 1, v[130:131]
	v_lshl_add_u64 v[162:163], v[154:155], 1, v[134:135]
	s_mov_b64 s[100:101], 0x210000
	v_lshl_add_u64 v[248:249], v[230:231], 0, s[100:101]
	s_mov_b64 s[100:101], 0x1000
	v_lshl_add_u64 v[250:251], v[248:249], 0, s[100:101]
	global_load_dwordx4 v[196:199], v[248:249], off
	global_load_dwordx4 v[200:203], v[250:251], off
	global_load_dwordx4 v[204:207], v[248:249], off offset:256
	global_load_dwordx4 v[208:211], v[250:251], off offset:256
	s_nop 1
	s_and_b64 vcc, exec, s[44:45]
	v_lshl_add_u64 v[160:161], s[24:25], 1, v[130:131]
	s_waitcnt vmcnt(11)
	s_nop 1
	v_mov_b64_e32 v[176:177], v[232:233]
	v_mov_b64_e32 v[178:179], v[234:235]
	v_lshlrev_b32_e32 v168, 16, v176
	v_and_b32_e32 v169, 0xffff0000, v176
	v_lshlrev_b32_e32 v166, 16, v177
	v_and_b32_e32 v167, 0xffff0000, v177
	v_lshlrev_b32_e32 v170, 16, v178
	v_and_b32_e32 v171, 0xffff0000, v178
	v_lshlrev_b32_e32 v164, 16, v179
	v_and_b32_e32 v165, 0xffff0000, v179
	s_cbranch_vccnz .LBB0_1649
	v_lshl_add_u64 v[130:131], v[154:155], 1, v[160:161]
	s_nop 1
	s_waitcnt vmcnt(10)
	s_nop 1
	v_mov_b64_e32 v[176:177], v[236:237]
	v_mov_b64_e32 v[178:179], v[238:239]
	v_lshlrev_b32_e32 v130, 16, v176
	v_and_b32_e32 v131, 0xffff0000, v176
	v_max_f32_e32 v130, v130, v130
	v_max_f32_e32 v131, v131, v131
	v_max_f32_e32 v130, 0xda24260, v130
	v_max_f32_e32 v131, 0xda24260, v131
	v_rcp_f32_e32 v130, v130
	v_rcp_f32_e32 v131, v131
	v_lshlrev_b32_e32 v134, 16, v177
	v_and_b32_e32 v135, 0xffff0000, v177
	v_lshlrev_b32_e32 v140, 16, v178
	v_pk_mul_f32 v[168:169], v[130:131], v[168:169]
	v_max_f32_e32 v130, v134, v134
	v_max_f32_e32 v131, v135, v135
	v_max_f32_e32 v130, 0xda24260, v130
	v_max_f32_e32 v131, 0xda24260, v131
	v_rcp_f32_e32 v130, v130
	v_rcp_f32_e32 v131, v131
	v_and_b32_e32 v141, 0xffff0000, v178
	v_lshlrev_b32_e32 v142, 16, v179
	v_and_b32_e32 v143, 0xffff0000, v179
	v_pk_mul_f32 v[166:167], v[130:131], v[166:167]
	v_max_f32_e32 v130, v140, v140
	v_max_f32_e32 v131, v141, v141
	v_max_f32_e32 v130, 0xda24260, v130
	v_max_f32_e32 v131, 0xda24260, v131
	v_rcp_f32_e32 v130, v130
	v_rcp_f32_e32 v131, v131
	s_nop 0
	v_pk_mul_f32 v[170:171], v[130:131], v[170:171]
	v_max_f32_e32 v130, v142, v142
	v_max_f32_e32 v131, v143, v143
	v_max_f32_e32 v130, 0xda24260, v130
	v_max_f32_e32 v131, 0xda24260, v131
	v_rcp_f32_e32 v130, v130
	v_rcp_f32_e32 v131, v131
	s_nop 0
	v_pk_mul_f32 v[164:165], v[130:131], v[164:165]

;     __device__ __forceinline__ void operator()(f32x4 (&acc)[2][2][4][2], const Unit& u, int wr, int wc, int fr, int fq) const {
;     ...
;             for (int m = 0; m < 4; ++m) { const size_t row = (size_t)(row0 + ai * HALF + m * 16);
; #pragma unroll
;                 for (int bj = 0; bj < 2; ++bj) { const int col = col0 + bj * HALF;
;                     const u32x4 g = *(const u32x4*)(PG + row * 6144 + br * D + col);
;                     float s[8] = {bflo(g[0]), bfhi(g[0]), bflo(g[1]), bfhi(g[1]), bflo(g[2]), bfhi(g[2]), bflo(g[3]), bfhi(g[3])};
;                     if (br < 2) { const u32x4 h = *(const u32x4*)(PG + row * 6144 + (br + 1) * D + col);
;                         const float d[8] = {bflo(h[0]), bfhi(h[0]), bflo(h[1]), bfhi(h[1]), bflo(h[2]), bfhi(h[2]), bflo(h[3]), bfhi(h[3])};
; #pragma unroll
;                         for (int j = 0; j < 8; ++j) s[j] = s[j] * __builtin_amdgcn_rcpf(fmaxf(d[j], 1e-30f)); }
;                     f32x4& v0 = acc[ai][bj][m][0]; f32x4& v1 = acc[ai][bj][m][1];
; #pragma unroll
;                     for (int j = 0; j < 4; ++j) { v0[j] *= s[j]; v1[j] *= s[4 + j]; }
.LBB0_1655:
	v_add_u32_e32 v158, 0xa0, v156
	v_mov_b64_e32 v[130:131], s[6:7]
	v_mad_i64_i32 v[130:131], s[2:3], v158, s13, v[130:131]
	v_lshl_add_u64 v[134:135], s[26:27], 1, v[130:131]
	v_lshl_add_u64 v[162:163], v[154:155], 1, v[134:135]
	s_nop 1
	s_and_b64 vcc, exec, s[44:45]
	v_lshl_add_u64 v[160:161], s[24:25], 1, v[130:131]
	s_waitcnt vmcnt(7)
	s_nop 1
	v_mov_b64_e32 v[176:177], v[180:181]
	v_mov_b64_e32 v[178:179], v[182:183]
	v_lshlrev_b32_e32 v168, 16, v176
	v_and_b32_e32 v169, 0xffff0000, v176
	v_lshlrev_b32_e32 v166, 16, v177
	v_and_b32_e32 v167, 0xffff0000, v177
	v_lshlrev_b32_e32 v170, 16, v178
	v_and_b32_e32 v171, 0xffff0000, v178
	v_lshlrev_b32_e32 v164, 16, v179
	v_and_b32_e32 v165, 0xffff0000, v179
	s_cbranch_vccnz .LBB0_1657
	v_lshl_add_u64 v[130:131], v[154:155], 1, v[160:161]
	s_nop 1
	s_waitcnt vmcnt(6)
	s_nop 1
	v_mov_b64_e32 v[176:177], v[184:185]
	v_mov_b64_e32 v[178:179], v[186:187]
	v_lshlrev_b32_e32 v130, 16, v176
	v_and_b32_e32 v131, 0xffff0000, v176
	v_max_f32_e32 v130, v130, v130
	v_max_f32_e32 v131, v131, v131
	v_max_f32_e32 v130, 0xda24260, v130
	v_max_f32_e32 v131, 0xda24260, v131
	v_rcp_f32_e32 v130, v130
	v_rcp_f32_e32 v131, v131
	v_lshlrev_b32_e32 v134, 16, v177
	v_and_b32_e32 v135, 0xffff0000, v177
	v_lshlrev_b32_e32 v140, 16, v178
	v_pk_mul_f32 v[168:169], v[130:131], v[168:169]
	v_max_f32_e32 v130, v134, v134
	v_max_f32_e32 v131, v135, v135
	v_max_f32_e32 v130, 0xda24260, v130
	v_max_f32_e32 v131, 0xda24260, v131
	v_rcp_f32_e32 v130, v130
	v_rcp_f32_e32 v131, v131
	v_and_b32_e32 v141, 0xffff0000, v178
	v_lshlrev_b32_e32 v142, 16, v179
	v_and_b32_e32 v143, 0xffff0000, v179
	v_pk_mul_f32 v[166:167], v[130:131], v[166:167]
	v_max_f32_e32 v130, v140, v140
	v_max_f32_e32 v131, v141, v141
	v_max_f32_e32 v130, 0xda24260, v130
	v_max_f32_e32 v131, 0xda24260, v131
	v_rcp_f32_e32 v130, v130
	v_rcp_f32_e32 v131, v131
	s_nop 0
	v_pk_mul_f32 v[170:171], v[130:131], v[170:171]
	v_max_f32_e32 v130, v142, v142
	v_max_f32_e32 v131, v143, v143
	v_max_f32_e32 v130, 0xda24260, v130
	v_max_f32_e32 v131, 0xda24260, v131
	v_rcp_f32_e32 v130, v130
	v_rcp_f32_e32 v131, v131
	s_nop 0
	v_pk_mul_f32 v[164:165], v[130:131], v[164:165]
